# diff-attention QK^T: K fragments prefetched into dead V-fragment registers with counted lgkmcnt; MFMA->VALU pad cut to 12 states
# speedup vs baseline: 1.0019x; 1.0019x over previous
; template <int KW, int DV, bool NA> ...
;     ...
;     auto stash = [&](int st, const u32x4 (&kreg)[NK], const u32x4 (&vreg)[NV]) {
;         unsigned char* Kt = lds + st * STAGE; unsigned char* Vt = Kt + 64 * KSTR;
; #pragma unroll
;         for (int e = 0; e < NK; ++e) { const int c = tid + 512 * e; *(u32x4*)(Kt + (c / KCH) * KSTR + (c % KCH) * 16) = kreg[e]; }
; #pragma unroll
;         for (int e = 0; e < NV; ++e) { const int c = tid + 512 * e; *(u32x4*)(Vt + (c / VCH) * VSTR + (c % VCH) * 16) = vreg[e]; }
;     };
;     ...
;     auto tile = [&](int i, const unsigned char* Kt, const unsigned char* Vt) {
;         constexpr int DT = DV / 32;
;         f32x16 p0, p1;
; #pragma unroll
;         for (int d0 = 0; d0 < 4; ++d0) {
;             const bf16x8 a0 = *(const bf16x8*)(Kt + q32 * KSTR + (kcoff + 16 * d0 + 8 * hi) * 2);
;             const bf16x8 a1 = *(const bf16x8*)(Kt + (32 + q32) * KSTR + (kcoff + 16 * d0 + 8 * hi) * 2);
;             if (d0 == 0) { p0 = __builtin_amdgcn_mfma_f32_32x32x16_bf16(a0, qf[0], negm, 0, 0, 0); p1 = __builtin_amdgcn_mfma_f32_32x32x16_bf16(a1, qf[0], negm, 0, 0, 0); }
;             else { p0 = __builtin_amdgcn_mfma_f32_32x32x16_bf16(a0, qf[d0], p0, 0, 0, 0); p1 = __builtin_amdgcn_mfma_f32_32x32x16_bf16(a1, qf[d0], p1, 0, 0, 0); }
;         }
;         if (NA && i < n1) {
;             const int kr = na_row0 + i, dr = kr - na_r + 7;
;             const int cs = min(max(na_c - 8, 0), 48);
;             const float* rb = rpbs + dr * 31 - na_c + 15;
; #pragma unroll
;             for (int r = 0; r < 16; ++r) {
;                 const int kc0 = (r & 3) + 8 * (r >> 2) + 4 * hi, kc1 = kc0 + 32;
;                 const bool ok0 = (kc0 >= cs) && (kc0 < cs + 16), ok1 = (kc1 >= cs) && (kc1 < cs + 16);
;                 p0[r] = ok0 ? p0[r] + rb[kc0] : -1e30f;
;                 p1[r] = ok1 ? p1[r] + rb[kc1] : -1e30f;
;             }
;         }
;         asm volatile("s_nop 15\n\ts_nop 7" : "+v"(p0), "+v"(p1));
;         float mxa = max3f_(p0[0], p0[1], p1[0]), mxb = max3f_(p0[2], p0[3], p1[1]);
;         mxa = max3f_(mxa, p1[2], p1[3]);
; #pragma unroll
;         for (int r = 4; r < 16; r += 4) { mxa = max3f_(mxa, p0[r], p0[r + 1]); mxb = max3f_(mxb, p0[r + 2], p0[r + 3]); mxa = max3f_(mxa, p1[r], p1[r + 1]); mxb = max3f_(mxb, p1[r + 2], p1[r + 3]); }
;         float mx = max3f_(mxa, mxb, mxb);
;         mx = xor32_max(mx);
.LBB0_388:
	s_mul_i32 s6, s2, 0x9400
	s_add_i32 s13, s6, 0
	v_add3_u32 v204, s13, v186, v187
	ds_read_b128 v[82:85], v204
	ds_read_b128 v[190:193], v204 offset:8704
	ds_read_b128 v[194:197], v204 offset:32
	ds_read_b128 v[198:201], v204 offset:8736
	ds_read_b128 v[206:209], v204 offset:64
	s_mul_i32 s6, s10, 0x9400
	s_add_i32 s12, s6, 0
	v_add3_u32 v98, s12, v179, v180
	s_waitcnt vmcnt(3)
	ds_write_b128 v98, v[130:133]
	v_add3_u32 v98, s12, v181, v183
	s_mov_b32 s11, s0
	s_xor_b64 s[0:1], s[4:5], -1
	s_waitcnt vmcnt(2)
	ds_write_b128 v98, v[134:137]
	v_add3_u32 v98, s12, v184, v180
	s_waitcnt vmcnt(1)
	ds_write_b128 v98, v[138:141] offset:17408
	v_add3_u32 v98, s12, v185, v183
	s_and_b64 vcc, exec, s[0:1]
	s_waitcnt vmcnt(0)
	ds_write_b128 v98, v[142:145] offset:17408
	s_cbranch_vccnz .LBB0_390
	global_load_dwordx4 v[130:133], v[168:169], off
	global_load_dwordx4 v[134:137], v[170:171], off
	global_load_dwordx4 v[138:141], v[172:173], off
	global_load_dwordx4 v[142:145], v[174:175], off
.LBB0_390:
	s_and_b64 vcc, exec, s[0:1]
	s_waitcnt lgkmcnt(8)
	v_mfma_f32_32x32x16_bf16 v[98:113], v[82:85], v[114:117], v[66:81]
	s_waitcnt lgkmcnt(7)
	v_mfma_f32_32x32x16_bf16 v[82:97], v[190:193], v[114:117], v[66:81]
	ds_read_b128 v[190:193], v204 offset:8768
	s_waitcnt lgkmcnt(7)
	v_mfma_f32_32x32x16_bf16 v[98:113], v[194:197], v[118:121], v[98:113]
	ds_read_b128 v[194:197], v204 offset:96
	s_waitcnt lgkmcnt(7)
	v_mfma_f32_32x32x16_bf16 v[82:97], v[198:201], v[118:121], v[82:97]
	ds_read_b128 v[198:201], v204 offset:8800
	s_waitcnt lgkmcnt(7)
	v_mfma_f32_32x32x16_bf16 v[98:113], v[206:209], v[122:125], v[98:113]
	s_waitcnt lgkmcnt(2)
	v_mfma_f32_32x32x16_bf16 v[82:97], v[190:193], v[122:125], v[82:97]
	s_waitcnt lgkmcnt(1)
	v_mfma_f32_32x32x16_bf16 v[98:113], v[194:197], v[126:129], v[98:113]
	s_waitcnt lgkmcnt(0)
	v_mfma_f32_32x32x16_bf16 v[82:97], v[198:201], v[126:129], v[82:97]
	s_nop 10
	s_nop 0
	v_max3_f32 v190, v98, v99, v82
	v_max3_f32 v191, v100, v101, v83
	s_nop 0
	v_max3_f32 v190, v190, v84, v85
	v_max3_f32 v191, v191, v104, v105
	s_nop 0
	v_max3_f32 v190, v190, v102, v103
	v_max3_f32 v191, v191, v88, v89
	s_nop 0
	v_max3_f32 v190, v190, v86, v87
	v_max3_f32 v191, v191, v108, v109
	s_nop 0
	v_max3_f32 v190, v190, v106, v107
	v_max3_f32 v191, v191, v92, v93
	s_nop 0
	v_max3_f32 v190, v190, v90, v91
	v_max3_f32 v191, v191, v112, v113
	s_nop 0
	v_max3_f32 v190, v190, v110, v111
	v_max3_f32 v191, v191, v96, v97
	s_nop 0
	v_max3_f32 v190, v190, v94, v95
	s_nop 0
	v_max3_f32 v190, v190, v191, v191
	s_nop 0
	v_mov_b32_e32 v191, v190
	s_nop 1
	v_permlane32_swap_b32_e32 v190, v191
	v_max_f32_e32 v191, v191, v191
	v_max_f32_e32 v190, v190, v190
	v_max_f32_e32 v190, v190, v191
	s_cbranch_vccz .LBB0_392
	v_cmp_lt_f32_e32 vcc, s80, v190
	s_cmp_lg_u64 vcc, 0
	s_cselect_b64 s[6:7], -1, 0
	s_cbranch_execz .LBB0_393
	s_branch .LBB0_394

; template <int KW, int DV, bool NA> ...
;     ...
;     auto tile = [&](int i, const unsigned char* Kt, const unsigned char* Vt) {
;         constexpr int DT = DV / 32;
;         f32x16 p0, p1;
; #pragma unroll
;         for (int d0 = 0; d0 < 4; ++d0) {
;             const bf16x8 a0 = *(const bf16x8*)(Kt + q32 * KSTR + (kcoff + 16 * d0 + 8 * hi) * 2);
;             const bf16x8 a1 = *(const bf16x8*)(Kt + (32 + q32) * KSTR + (kcoff + 16 * d0 + 8 * hi) * 2);
;             if (d0 == 0) { p0 = __builtin_amdgcn_mfma_f32_32x32x16_bf16(a0, qf[0], negm, 0, 0, 0); p1 = __builtin_amdgcn_mfma_f32_32x32x16_bf16(a1, qf[0], negm, 0, 0, 0); }
;             else { p0 = __builtin_amdgcn_mfma_f32_32x32x16_bf16(a0, qf[d0], p0, 0, 0, 0); p1 = __builtin_amdgcn_mfma_f32_32x32x16_bf16(a1, qf[d0], p1, 0, 0, 0); }
;         }
;         if (NA && i < n1) {
;             const int kr = na_row0 + i, dr = kr - na_r + 7;
;             const int cs = min(max(na_c - 8, 0), 48);
;             const float* rb = rpbs + dr * 31 - na_c + 15;
; #pragma unroll
;             for (int r = 0; r < 16; ++r) {
;                 const int kc0 = (r & 3) + 8 * (r >> 2) + 4 * hi, kc1 = kc0 + 32;
;                 const bool ok0 = (kc0 >= cs) && (kc0 < cs + 16), ok1 = (kc1 >= cs) && (kc1 < cs + 16);
;                 p0[r] = ok0 ? p0[r] + rb[kc0] : -1e30f;
;                 p1[r] = ok1 ? p1[r] + rb[kc1] : -1e30f;
;             }
;         }
;         asm volatile("s_nop 15\n\ts_nop 7" : "+v"(p0), "+v"(p1));
;         float mxa = max3f_(p0[0], p0[1], p1[0]), mxb = max3f_(p0[2], p0[3], p1[1]);
;         mxa = max3f_(mxa, p1[2], p1[3]);
; #pragma unroll
;         for (int r = 4; r < 16; r += 4) { mxa = max3f_(mxa, p0[r], p0[r + 1]); mxb = max3f_(mxb, p0[r + 2], p0[r + 3]); mxa = max3f_(mxa, p1[r], p1[r + 1]); mxb = max3f_(mxb, p1[r + 2], p1[r + 3]); }
;         float mx = max3f_(mxa, mxb, mxb);
;         mx = xor32_max(mx);
;         if (first || __any(mx > 6.f)) {
;             const float dl = first ? mx : fmaxf(mx, 0.f);
;             const float f = first ? 0.f : __builtin_amdgcn_exp2f(-dl);
;             m_ref += dl; l_run *= f;
; #pragma unroll
;             for (int r = 0; r < 16; ++r) negm[r] = -m_ref;
;             asm volatile("" : "+v"(negm));
; #pragma unroll
;             for (int r = 0; r < 16; ++r) { p0[r] -= dl; p1[r] -= dl; }
; #pragma unroll
;             for (int d = 0; d < DT; ++d)
; #pragma unroll
.LBB0_398:
	v_add3_u32 v204, s12, v186, v187
	ds_read_b128 v[210:213], v204
	ds_read_b128 v[190:193], v204 offset:8704
	ds_read_b128 v[194:197], v204 offset:32
	ds_read_b128 v[198:201], v204 offset:8736
	ds_read_b128 v[206:209], v204 offset:64
	v_add_f32_e32 v98, 0, v98
	v_add_f32_e32 v98, v99, v98
	v_add_f32_e32 v98, v100, v98
	v_add_f32_e32 v98, v101, v98
	v_add_f32_e32 v98, v102, v98
	v_add_f32_e32 v98, v103, v98
	v_add_f32_e32 v98, v104, v98
	v_add_f32_e32 v98, v105, v98
	v_add_f32_e32 v98, v106, v98
	v_add_f32_e32 v98, v107, v98
	v_add_f32_e32 v98, v108, v98
	v_add_f32_e32 v98, v109, v98
	v_add_f32_e32 v98, v110, v98
	v_add_f32_e32 v98, v111, v98
	v_add_f32_e32 v98, v112, v98
	v_add_f32_e32 v98, v113, v98
	v_add_f32_e32 v82, v82, v98
	v_add_f32_e32 v82, v83, v82
	v_add_f32_e32 v82, v84, v82
	v_add_f32_e32 v82, v85, v82
	v_add_f32_e32 v82, v86, v82
	v_add_f32_e32 v82, v87, v82
	v_add_f32_e32 v82, v88, v82
	v_add_f32_e32 v82, v89, v82
	v_add_f32_e32 v82, v90, v82
	v_add_f32_e32 v82, v91, v82
	v_add_f32_e32 v82, v92, v82
	v_add_f32_e32 v82, v93, v82
	v_add_f32_e32 v82, v94, v82
	v_add_f32_e32 v82, v95, v82
	v_add_f32_e32 v82, v96, v82
	v_add_f32_e32 v82, v97, v82
	v_add_f32_e32 v189, v189, v82
	s_waitcnt lgkmcnt(4)
	v_mfma_f32_32x32x16_bf16 v[98:113], v[210:213], v[114:117], v[66:81]
	s_waitcnt lgkmcnt(3)
	v_mfma_f32_32x32x16_bf16 v[82:97], v[190:193], v[114:117], v[66:81]
	ds_read_b128 v[190:193], v204 offset:8768
	s_waitcnt lgkmcnt(3)
	v_mfma_f32_32x32x16_bf16 v[98:113], v[194:197], v[118:121], v[98:113]
	ds_read_b128 v[194:197], v204 offset:96
	s_waitcnt lgkmcnt(3)
	v_mfma_f32_32x32x16_bf16 v[82:97], v[198:201], v[118:121], v[82:97]
	ds_read_b128 v[198:201], v204 offset:8800
	s_waitcnt lgkmcnt(3)
	v_mfma_f32_32x32x16_bf16 v[98:113], v[206:209], v[122:125], v[98:113]
	s_waitcnt lgkmcnt(2)
	v_mfma_f32_32x32x16_bf16 v[82:97], v[190:193], v[122:125], v[82:97]
	s_waitcnt lgkmcnt(1)
	v_mfma_f32_32x32x16_bf16 v[98:113], v[194:197], v[126:129], v[98:113]
	s_waitcnt lgkmcnt(0)
	v_mfma_f32_32x32x16_bf16 v[82:97], v[198:201], v[126:129], v[82:97]
	s_nop 10
	s_nop 0
	v_max3_f32 v190, v98, v99, v82
	v_max3_f32 v191, v100, v101, v83
	s_nop 0
	v_max3_f32 v190, v190, v84, v85
	v_max3_f32 v191, v191, v104, v105
	s_nop 0
	v_max3_f32 v190, v190, v102, v103
	v_max3_f32 v191, v191, v88, v89
	s_nop 0
	v_max3_f32 v190, v190, v86, v87
	v_max3_f32 v191, v191, v108, v109
	s_nop 0
	v_max3_f32 v190, v190, v106, v107
	v_max3_f32 v191, v191, v92, v93
	s_nop 0
	v_max3_f32 v190, v190, v90, v91
	v_max3_f32 v191, v191, v112, v113
	s_nop 0
	v_max3_f32 v190, v190, v110, v111
	v_max3_f32 v191, v191, v96, v97
	s_nop 0
	v_max3_f32 v190, v190, v94, v95
	s_nop 0
	v_max3_f32 v190, v190, v191, v191
	s_nop 0
	v_mov_b32_e32 v191, v190
	s_nop 1
	v_permlane32_swap_b32_e32 v190, v191
	v_max_f32_e32 v191, v191, v191
	v_max_f32_e32 v190, v190, v190
	v_max_f32_e32 v190, v190, v191
	v_cmp_lt_f32_e32 vcc, s80, v190
	s_cbranch_vccz .LBB0_400
	v_max_f32_e32 v66, v190, v190
	v_max_f32_e32 v190, 0, v66
	v_exp_f32_e64 v192, -v190
	v_add_f32_e32 v0, v0, v190
	v_xor_b32_e32 v66, 0x80000000, v0
	v_mov_b32_e32 v67, v66
	v_mul_f32_e32 v189, v189, v192
	v_mov_b32_e32 v68, v66
	v_mov_b32_e32 v69, v66
	v_mov_b32_e32 v70, v66
	v_mov_b32_e32 v71, v66
	v_mov_b32_e32 v72, v66
	v_mov_b32_e32 v73, v66
	v_mov_b32_e32 v74, v66
	v_mov_b32_e32 v75, v66
	v_mov_b32_e32 v76, v66
	v_mov_b32_e32 v77, v66
	v_mov_b32_e32 v78, v66
	v_mov_b32_e32 v79, v66
	v_mov_b32_e32 v80, v66
	v_mov_b32_e32 v81, v66
	v_pk_add_f32 v[98:99], v[98:99], v[190:191] op_sel_hi:[1,0] neg_lo:[0,1] neg_hi:[0,1]
	v_pk_add_f32 v[82:83], v[82:83], v[190:191] op_sel_hi:[1,0] neg_lo:[0,1] neg_hi:[0,1]
	v_pk_add_f32 v[100:101], v[100:101], v[190:191] op_sel_hi:[1,0] neg_lo:[0,1] neg_hi:[0,1]
	v_pk_add_f32 v[84:85], v[84:85], v[190:191] op_sel_hi:[1,0] neg_lo:[0,1] neg_hi:[0,1]
	v_pk_add_f32 v[102:103], v[102:103], v[190:191] op_sel_hi:[1,0] neg_lo:[0,1] neg_hi:[0,1]
	v_pk_add_f32 v[86:87], v[86:87], v[190:191] op_sel_hi:[1,0] neg_lo:[0,1] neg_hi:[0,1]
	v_pk_add_f32 v[104:105], v[104:105], v[190:191] op_sel_hi:[1,0] neg_lo:[0,1] neg_hi:[0,1]
	v_pk_add_f32 v[88:89], v[88:89], v[190:191] op_sel_hi:[1,0] neg_lo:[0,1] neg_hi:[0,1]
	v_pk_add_f32 v[106:107], v[106:107], v[190:191] op_sel_hi:[1,0] neg_lo:[0,1] neg_hi:[0,1]
	v_pk_add_f32 v[90:91], v[90:91], v[190:191] op_sel_hi:[1,0] neg_lo:[0,1] neg_hi:[0,1]
	v_pk_add_f32 v[108:109], v[108:109], v[190:191] op_sel_hi:[1,0] neg_lo:[0,1] neg_hi:[0,1]
	v_pk_add_f32 v[92:93], v[92:93], v[190:191] op_sel_hi:[1,0] neg_lo:[0,1] neg_hi:[0,1]
	v_pk_add_f32 v[110:111], v[110:111], v[190:191] op_sel_hi:[1,0] neg_lo:[0,1] neg_hi:[0,1]
	v_pk_add_f32 v[94:95], v[94:95], v[190:191] op_sel_hi:[1,0] neg_lo:[0,1] neg_hi:[0,1]
	v_pk_add_f32 v[112:113], v[112:113], v[190:191] op_sel_hi:[1,0] neg_lo:[0,1] neg_hi:[0,1]
	v_pk_add_f32 v[96:97], v[96:97], v[190:191] op_sel_hi:[1,0] neg_lo:[0,1] neg_hi:[0,1]
	v_pk_mul_f32 v[64:65], v[64:65], v[192:193] op_sel_hi:[1,0]
	v_pk_mul_f32 v[62:63], v[62:63], v[192:193] op_sel_hi:[1,0]
	v_pk_mul_f32 v[60:61], v[60:61], v[192:193] op_sel_hi:[1,0]
	v_pk_mul_f32 v[58:59], v[58:59], v[192:193] op_sel_hi:[1,0]
	v_pk_mul_f32 v[56:57], v[56:57], v[192:193] op_sel_hi:[1,0]
	v_pk_mul_f32 v[54:55], v[54:55], v[192:193] op_sel_hi:[1,0]
	v_pk_mul_f32 v[52:53], v[52:53], v[192:193] op_sel_hi:[1,0]
	v_pk_mul_f32 v[50:51], v[50:51], v[192:193] op_sel_hi:[1,0]
	v_pk_mul_f32 v[48:49], v[48:49], v[192:193] op_sel_hi:[1,0]
	v_pk_mul_f32 v[46:47], v[46:47], v[192:193] op_sel_hi:[1,0]
	v_pk_mul_f32 v[44:45], v[44:45], v[192:193] op_sel_hi:[1,0]
	v_pk_mul_f32 v[42:43], v[42:43], v[192:193] op_sel_hi:[1,0]
	v_pk_mul_f32 v[40:41], v[40:41], v[192:193] op_sel_hi:[1,0]
	v_pk_mul_f32 v[38:39], v[38:39], v[192:193] op_sel_hi:[1,0]
	v_pk_mul_f32 v[36:37], v[36:37], v[192:193] op_sel_hi:[1,0]
	v_pk_mul_f32 v[34:35], v[34:35], v[192:193] op_sel_hi:[1,0]
	v_pk_mul_f32 v[32:33], v[32:33], v[192:193] op_sel_hi:[1,0]
	v_pk_mul_f32 v[30:31], v[30:31], v[192:193] op_sel_hi:[1,0]
	v_pk_mul_f32 v[28:29], v[28:29], v[192:193] op_sel_hi:[1,0]
	v_pk_mul_f32 v[26:27], v[26:27], v[192:193] op_sel_hi:[1,0]
	v_pk_mul_f32 v[24:25], v[24:25], v[192:193] op_sel_hi:[1,0]
	v_pk_mul_f32 v[22:23], v[22:23], v[192:193] op_sel_hi:[1,0]
	v_pk_mul_f32 v[20:21], v[20:21], v[192:193] op_sel_hi:[1,0]
	v_pk_mul_f32 v[18:19], v[18:19], v[192:193] op_sel_hi:[1,0]
	v_pk_mul_f32 v[16:17], v[16:17], v[192:193] op_sel_hi:[1,0]
	v_pk_mul_f32 v[14:15], v[14:15], v[192:193] op_sel_hi:[1,0]
	v_pk_mul_f32 v[12:13], v[12:13], v[192:193] op_sel_hi:[1,0]
	v_pk_mul_f32 v[10:11], v[10:11], v[192:193] op_sel_hi:[1,0]
	v_pk_mul_f32 v[8:9], v[8:9], v[192:193] op_sel_hi:[1,0]
	v_pk_mul_f32 v[6:7], v[6:7], v[192:193] op_sel_hi:[1,0]
	v_pk_mul_f32 v[4:5], v[4:5], v[192:193] op_sel_hi:[1,0]
	v_pk_mul_f32 v[2:3], v[2:3], v[192:193] op_sel_hi:[1,0]
